# attention loop v2: 12-slot fragment ring, SGPR-base direct-to-LDS loads issued in MFMA gaps, MFMA-first after barrier, tile-max shuffle off critical path
# speedup vs baseline: 1.0530x; 1.0210x over previous
.Latt_entry:
	v_mov_b32_e32 v243, 0
	v_add_u32_e32 v239, v228, v229
	v_add_u32_e32 v240, v228, v231
	v_add_u32_e32 v241, v228, v233
	v_add_u32_e32 v242, v228, v235
	s_mov_b64 s[6:7], 0xe804000
	v_lshl_add_u64 v[244:245], v[180:181], 0, s[0:1]
	v_lshl_add_u64 v[244:245], v[244:245], 0, s[6:7]
	s_mov_b64 s[6:7], 0x10880080
	v_lshl_add_u64 v[246:247], v[184:185], 0, s[0:1]
	v_lshl_add_u64 v[246:247], v[246:247], 0, s[6:7]
	v_readfirstlane_b32 s7, v0
	v_readfirstlane_b32 s0, v244
	v_readfirstlane_b32 s1, v245
	v_readfirstlane_b32 s2, v246
	v_readfirstlane_b32 s3, v247
	s_and_b32 s0, s0, 0xffffff80
	s_and_b32 s2, s2, 0xffffff80
	s_nop 0
	v_subrev_u32_e32 v223, s0, v244
	v_subrev_u32_e32 v224, s2, v246
	s_nop 4
	ds_read_b128 v[180:183], v230 offset:16384
	ds_read_b128 v[130:133], v234 offset:16384
	v_exp_f32_e32 v98, v98
	v_exp_f32_e32 v99, v99
	v_add_f32_e32 v247, 0, v98
	v_add_f32_e32 v247, v99, v247
	ds_read_b128 v[184:187], v230 offset:20480
	ds_read_b128 v[134:137], v234 offset:20480
	v_exp_f32_e32 v100, v100
	v_exp_f32_e32 v101, v101
	v_add_f32_e32 v247, v100, v247
	v_add_f32_e32 v247, v101, v247
	ds_read_b128 v[188:191], v232 offset:16384
	ds_read_b128 v[138:141], v236 offset:16384
	s_mov_b32 m0, s7
	s_add_u32 s4, s0, 0x208000
	s_addc_u32 s5, s1, 0
	global_load_lds_dwordx4 v223, s[0:1]
	v_exp_f32_e32 v102, v102
	v_exp_f32_e32 v103, v103
	v_add_f32_e32 v247, v102, v247
	v_add_f32_e32 v247, v103, v247
	ds_read_b128 v[192:195], v232 offset:20480
	ds_read_b128 v[142:145], v236 offset:20480
	s_add_u32 m0, s7, 0x2000
	s_add_u32 s0, s0, 0x2000
	s_addc_u32 s1, s1, 0
	global_load_lds_dwordx4 v223, s[4:5]
	v_exp_f32_e32 v104, v104
	v_exp_f32_e32 v105, v105
	v_add_f32_e32 v247, v104, v247
	v_add_f32_e32 v247, v105, v247
	ds_read_b128 v[200:203], v239 offset:32768
	s_add_u32 m0, s7, 0xc000
	s_add_u32 s4, s2, 0x208000
	s_addc_u32 s5, s3, 0
	global_load_lds_dwordx4 v224, s[2:3]
	v_exp_f32_e32 v106, v106
	v_exp_f32_e32 v107, v107
	v_add_f32_e32 v247, v106, v247
	v_add_f32_e32 v247, v107, v247
	ds_read_b128 v[204:207], v239 offset:36864
	s_add_u32 m0, s7, 0xe000
	s_add_u32 s2, s2, 0x80
	s_addc_u32 s3, s3, 0
	global_load_lds_dwordx4 v224, s[4:5]
	v_exp_f32_e32 v108, v108
	v_exp_f32_e32 v109, v109
	v_add_f32_e32 v247, v108, v247
	v_add_f32_e32 v247, v109, v247
	ds_read_b128 v[208:211], v239 offset:40960
	v_exp_f32_e32 v110, v110
	v_exp_f32_e32 v111, v111
	v_add_f32_e32 v247, v110, v247
	v_add_f32_e32 v247, v111, v247
	ds_read_b128 v[212:215], v239 offset:45056
	v_exp_f32_e32 v112, v112
	v_exp_f32_e32 v113, v113
	v_add_f32_e32 v247, v112, v247
	v_add_f32_e32 v247, v113, v247
	s_branch .Latt_A_segD

.Latt_A_go:
	v_mfma_f32_32x32x16_bf16 v[2:17], v[130:133], v[114:117], v[2:17]
	ds_read_b128 v[180:183], v230 offset:16384
	ds_read_b128 v[130:133], v234 offset:16384
	v_exp_f32_e32 v98, v98
	v_exp_f32_e32 v99, v99
	v_add_f32_e32 v247, 0, v98
	v_add_f32_e32 v247, v99, v247
	v_mfma_f32_32x32x16_bf16 v[50:65], v[134:137], v[114:117], v[50:65]
	ds_read_b128 v[184:187], v230 offset:20480
	ds_read_b128 v[134:137], v234 offset:20480
	v_exp_f32_e32 v100, v100
	v_exp_f32_e32 v101, v101
	v_add_f32_e32 v247, v100, v247
	v_add_f32_e32 v247, v101, v247
	v_mfma_f32_32x32x16_bf16 v[34:49], v[138:141], v[114:117], v[34:49]
	ds_read_b128 v[188:191], v232 offset:16384
	ds_read_b128 v[138:141], v236 offset:16384
	s_mov_b32 m0, s7
	s_add_u32 s4, s0, 0x208000
	s_addc_u32 s5, s1, 0
	global_load_lds_dwordx4 v223, s[0:1]
	v_exp_f32_e32 v102, v102
	v_exp_f32_e32 v103, v103
	v_add_f32_e32 v247, v102, v247
	v_add_f32_e32 v247, v103, v247
	v_mfma_f32_32x32x16_bf16 v[18:33], v[142:145], v[114:117], v[18:33]
	ds_read_b128 v[192:195], v232 offset:20480
	ds_read_b128 v[142:145], v236 offset:20480
	s_add_u32 m0, s7, 0x2000
	s_add_u32 s0, s0, 0x2000
	s_addc_u32 s1, s1, 0
	global_load_lds_dwordx4 v223, s[4:5]
	v_exp_f32_e32 v104, v104
	v_exp_f32_e32 v105, v105
	v_add_f32_e32 v247, v104, v247
	v_add_f32_e32 v247, v105, v247
	v_mfma_f32_32x32x16_bf16 v[2:17], v[200:203], v[118:121], v[2:17]
	ds_read_b128 v[200:203], v239 offset:32768
	s_add_u32 m0, s7, 0xc000
	s_add_u32 s4, s2, 0x208000
	s_addc_u32 s5, s3, 0
	global_load_lds_dwordx4 v224, s[2:3]
	v_exp_f32_e32 v106, v106
	v_exp_f32_e32 v107, v107
	v_add_f32_e32 v247, v106, v247
	v_add_f32_e32 v247, v107, v247
	v_mfma_f32_32x32x16_bf16 v[50:65], v[204:207], v[118:121], v[50:65]
	ds_read_b128 v[204:207], v239 offset:36864
	s_add_u32 m0, s7, 0xe000
	s_add_u32 s2, s2, 0x80
	s_addc_u32 s3, s3, 0
	global_load_lds_dwordx4 v224, s[4:5]
	v_exp_f32_e32 v108, v108
	v_exp_f32_e32 v109, v109
	v_add_f32_e32 v247, v108, v247
	v_add_f32_e32 v247, v109, v247
	v_mfma_f32_32x32x16_bf16 v[34:49], v[208:211], v[118:121], v[34:49]
	ds_read_b128 v[208:211], v239 offset:40960
	v_exp_f32_e32 v110, v110
	v_exp_f32_e32 v111, v111
	v_add_f32_e32 v247, v110, v247
	v_add_f32_e32 v247, v111, v247
	v_mfma_f32_32x32x16_bf16 v[18:33], v[212:215], v[118:121], v[18:33]
	ds_read_b128 v[212:215], v239 offset:45056
	v_exp_f32_e32 v112, v112
	v_exp_f32_e32 v113, v113
	v_add_f32_e32 v247, v112, v247
	v_add_f32_e32 v247, v113, v247
	v_cmp_lt_f32_e32 vcc, s26, v243
	s_cbranch_vccnz .Latt_A_rare2
.Latt_A_segD:
	s_waitcnt lgkmcnt(11)
	v_mfma_f32_32x32x16_bf16 v[146:161], v[180:183], v[162:165], v[82:97]
	ds_read_b128 v[180:183], v240 offset:32768
	v_exp_f32_e32 v66, v66
	v_cvt_pk_bf16_f32 v98, v98, v99
	v_add_f32_e32 v247, v66, v247
	s_waitcnt lgkmcnt(10)
	v_mfma_f32_32x32x16_bf16 v[114:129], v[184:187], v[162:165], v[82:97]
	ds_read_b128 v[184:187], v240 offset:36864
	v_exp_f32_e32 v67, v67
	v_cvt_pk_bf16_f32 v99, v100, v101
	v_add_f32_e32 v247, v67, v247
	s_waitcnt lgkmcnt(9)
	v_mfma_f32_32x32x16_bf16 v[146:161], v[188:191], v[166:169], v[146:161]
	ds_read_b128 v[188:191], v240 offset:40960
	v_exp_f32_e32 v68, v68
	v_cvt_pk_bf16_f32 v100, v102, v103
	v_add_f32_e32 v247, v68, v247
	s_waitcnt lgkmcnt(8)
	v_mfma_f32_32x32x16_bf16 v[114:129], v[192:195], v[166:169], v[114:129]
	ds_read_b128 v[192:195], v240 offset:45056
	v_exp_f32_e32 v69, v69
	v_cvt_pk_bf16_f32 v101, v104, v105
	v_add_f32_e32 v247, v69, v247
	s_waitcnt lgkmcnt(14)
	v_mfma_f32_32x32x16_bf16 v[146:161], v[130:133], v[170:173], v[146:161]
	ds_read_b128 v[130:133], v241 offset:32768
	v_exp_f32_e32 v70, v70
	v_cvt_pk_bf16_f32 v102, v106, v107
	v_add_f32_e32 v247, v70, v247
	s_waitcnt lgkmcnt(13)
	v_mfma_f32_32x32x16_bf16 v[114:129], v[134:137], v[170:173], v[114:129]
	ds_read_b128 v[134:137], v241 offset:36864
	v_exp_f32_e32 v71, v71
	v_cvt_pk_bf16_f32 v103, v108, v109
	v_add_f32_e32 v247, v71, v247
	s_waitcnt lgkmcnt(12)
	v_mfma_f32_32x32x16_bf16 v[146:161], v[138:141], v[174:177], v[146:161]
	ds_read_b128 v[138:141], v241 offset:40960
	v_exp_f32_e32 v72, v72
	v_cvt_pk_bf16_f32 v104, v110, v111
	v_add_f32_e32 v247, v72, v247
	s_waitcnt lgkmcnt(11)
	v_mfma_f32_32x32x16_bf16 v[114:129], v[142:145], v[174:177], v[114:129]
	ds_read_b128 v[142:145], v241 offset:45056
	v_exp_f32_e32 v73, v73
	v_cvt_pk_bf16_f32 v105, v112, v113
	v_add_f32_e32 v247, v73, v247
	s_waitcnt lgkmcnt(11)
	v_mfma_f32_32x32x16_bf16 v[2:17], v[200:203], v[98:101], v[2:17]
	ds_read_b128 v[200:203], v242 offset:32768
	v_exp_f32_e32 v74, v74
	v_exp_f32_e32 v75, v75
	v_add_f32_e32 v247, v74, v247
	v_add_f32_e32 v247, v75, v247
	s_waitcnt lgkmcnt(11)
	v_mfma_f32_32x32x16_bf16 v[50:65], v[204:207], v[98:101], v[50:65]
	ds_read_b128 v[204:207], v242 offset:36864
	v_exp_f32_e32 v76, v76
	v_exp_f32_e32 v77, v77
	v_add_f32_e32 v247, v76, v247
	v_add_f32_e32 v247, v77, v247
	s_waitcnt lgkmcnt(11)
	v_mfma_f32_32x32x16_bf16 v[34:49], v[208:211], v[98:101], v[34:49]
	ds_read_b128 v[208:211], v242 offset:40960
	v_exp_f32_e32 v78, v78
	v_exp_f32_e32 v79, v79
	v_add_f32_e32 v247, v78, v247
	v_add_f32_e32 v247, v79, v247
	s_waitcnt lgkmcnt(11)
	v_mfma_f32_32x32x16_bf16 v[18:33], v[212:215], v[98:101], v[18:33]
	ds_read_b128 v[212:215], v242 offset:45056
	v_max_i32_e32 v244, v146, v114
	ds_bpermute_b32 v245, v222, v244
	v_exp_f32_e32 v80, v80
	v_exp_f32_e32 v81, v81
	v_add_f32_e32 v247, v80, v247
	v_add_f32_e32 v247, v81, v247
	s_waitcnt lgkmcnt(12)
	v_mfma_f32_32x32x16_bf16 v[2:17], v[180:183], v[102:105], v[2:17]
	v_cvt_pk_bf16_f32 v66, v66, v67
	v_cvt_pk_bf16_f32 v67, v68, v69
	s_waitcnt lgkmcnt(11)
	v_mfma_f32_32x32x16_bf16 v[50:65], v[184:187], v[102:105], v[50:65]
	v_cvt_pk_bf16_f32 v68, v70, v71
	v_cvt_pk_bf16_f32 v69, v72, v73
	s_waitcnt lgkmcnt(10)
	v_mfma_f32_32x32x16_bf16 v[34:49], v[188:191], v[102:105], v[34:49]
	v_cvt_pk_bf16_f32 v70, v74, v75
	v_cvt_pk_bf16_f32 v71, v76, v77
	s_waitcnt lgkmcnt(9)
	v_mfma_f32_32x32x16_bf16 v[18:33], v[192:195], v[102:105], v[18:33]
	v_cvt_pk_bf16_f32 v72, v78, v79
	v_cvt_pk_bf16_f32 v73, v80, v81
	v_add_f32_e32 v238, v238, v247
	s_waitcnt vmcnt(0) lgkmcnt(0)
	v_max_i32_e32 v246, v244, v245
	s_barrier
	v_cmp_lt_f32_e32 vcc, s26, v246
	s_cbranch_vccnz .Latt_B_rare1
.Latt_B_go:
	v_mfma_f32_32x32x16_bf16 v[2:17], v[130:133], v[66:69], v[2:17]
	ds_read_b128 v[180:183], v230 offset:0
	ds_read_b128 v[130:133], v234 offset:0
	v_exp_f32_e32 v146, v146
	v_exp_f32_e32 v147, v147
	v_add_f32_e32 v247, 0, v146
	v_add_f32_e32 v247, v147, v247
	v_mfma_f32_32x32x16_bf16 v[50:65], v[134:137], v[66:69], v[50:65]
	ds_read_b128 v[184:187], v230 offset:4096
	ds_read_b128 v[134:137], v234 offset:4096
	v_exp_f32_e32 v148, v148
	v_exp_f32_e32 v149, v149
	v_add_f32_e32 v247, v148, v247
	v_add_f32_e32 v247, v149, v247
	v_mfma_f32_32x32x16_bf16 v[34:49], v[138:141], v[66:69], v[34:49]
	ds_read_b128 v[188:191], v232 offset:0
	ds_read_b128 v[138:141], v236 offset:0
	s_add_u32 m0, s7, 0x4000
	s_add_u32 s4, s0, 0x208000
	s_addc_u32 s5, s1, 0
	global_load_lds_dwordx4 v223, s[0:1]
	v_exp_f32_e32 v150, v150
	v_exp_f32_e32 v151, v151
	v_add_f32_e32 v247, v150, v247
	v_add_f32_e32 v247, v151, v247
	v_mfma_f32_32x32x16_bf16 v[18:33], v[142:145], v[66:69], v[18:33]
	ds_read_b128 v[192:195], v232 offset:4096
	ds_read_b128 v[142:145], v236 offset:4096
	s_add_u32 m0, s7, 0x6000
	s_add_u32 s0, s0, 0x2000
	s_addc_u32 s1, s1, 0
	global_load_lds_dwordx4 v223, s[4:5]
	v_exp_f32_e32 v152, v152
	v_exp_f32_e32 v153, v153
	v_add_f32_e32 v247, v152, v247
	v_add_f32_e32 v247, v153, v247
	v_mfma_f32_32x32x16_bf16 v[2:17], v[200:203], v[70:73], v[2:17]
	ds_read_b128 v[200:203], v239 offset:49152
	s_add_u32 m0, s7, 0x8000
	s_add_u32 s4, s2, 0x208000
	s_addc_u32 s5, s3, 0
	global_load_lds_dwordx4 v224, s[2:3]
	v_exp_f32_e32 v154, v154
	v_exp_f32_e32 v155, v155
	v_add_f32_e32 v247, v154, v247
	v_add_f32_e32 v247, v155, v247
	v_mfma_f32_32x32x16_bf16 v[50:65], v[204:207], v[70:73], v[50:65]
	ds_read_b128 v[204:207], v239 offset:53248
	s_add_u32 m0, s7, 0xa000
	s_add_u32 s2, s2, 0x80
	s_addc_u32 s3, s3, 0
	global_load_lds_dwordx4 v224, s[4:5]
	v_exp_f32_e32 v156, v156
	v_exp_f32_e32 v157, v157
	v_add_f32_e32 v247, v156, v247
	v_add_f32_e32 v247, v157, v247
	v_mfma_f32_32x32x16_bf16 v[34:49], v[208:211], v[70:73], v[34:49]
	ds_read_b128 v[208:211], v239 offset:57344
	v_exp_f32_e32 v158, v158
	v_exp_f32_e32 v159, v159
	v_add_f32_e32 v247, v158, v247
	v_add_f32_e32 v247, v159, v247
	v_mfma_f32_32x32x16_bf16 v[18:33], v[212:215], v[70:73], v[18:33]
	ds_read_b128 v[212:215], v239 offset:61440
	v_exp_f32_e32 v160, v160
	v_exp_f32_e32 v161, v161
	v_add_f32_e32 v247, v160, v247
	v_add_f32_e32 v247, v161, v247
	v_cmp_lt_f32_e32 vcc, s26, v246
	s_cbranch_vccnz .Latt_B_rare2
.Latt_B_segD:
	s_waitcnt lgkmcnt(11)
	v_mfma_f32_32x32x16_bf16 v[98:113], v[180:183], v[162:165], v[82:97]
	ds_read_b128 v[180:183], v240 offset:49152
	v_exp_f32_e32 v114, v114
	v_cvt_pk_bf16_f32 v146, v146, v147
	v_add_f32_e32 v247, v114, v247
	s_waitcnt lgkmcnt(10)
	v_mfma_f32_32x32x16_bf16 v[66:81], v[184:187], v[162:165], v[82:97]
	ds_read_b128 v[184:187], v240 offset:53248
	v_exp_f32_e32 v115, v115
	v_cvt_pk_bf16_f32 v147, v148, v149
	v_add_f32_e32 v247, v115, v247
	s_waitcnt lgkmcnt(9)
	v_mfma_f32_32x32x16_bf16 v[98:113], v[188:191], v[166:169], v[98:113]
	ds_read_b128 v[188:191], v240 offset:57344
	v_exp_f32_e32 v116, v116
	v_cvt_pk_bf16_f32 v148, v150, v151
	v_add_f32_e32 v247, v116, v247
	s_waitcnt lgkmcnt(8)
	v_mfma_f32_32x32x16_bf16 v[66:81], v[192:195], v[166:169], v[66:81]
	ds_read_b128 v[192:195], v240 offset:61440
	v_exp_f32_e32 v117, v117
	v_cvt_pk_bf16_f32 v149, v152, v153
	v_add_f32_e32 v247, v117, v247
	s_waitcnt lgkmcnt(14)
	v_mfma_f32_32x32x16_bf16 v[98:113], v[130:133], v[170:173], v[98:113]
	ds_read_b128 v[130:133], v241 offset:49152
	v_exp_f32_e32 v118, v118
	v_cvt_pk_bf16_f32 v150, v154, v155
	v_add_f32_e32 v247, v118, v247
	s_waitcnt lgkmcnt(13)
	v_mfma_f32_32x32x16_bf16 v[66:81], v[134:137], v[170:173], v[66:81]
	ds_read_b128 v[134:137], v241 offset:53248
	v_exp_f32_e32 v119, v119
	v_cvt_pk_bf16_f32 v151, v156, v157
	v_add_f32_e32 v247, v119, v247
	s_waitcnt lgkmcnt(12)
	v_mfma_f32_32x32x16_bf16 v[98:113], v[138:141], v[174:177], v[98:113]
	ds_read_b128 v[138:141], v241 offset:57344
	v_exp_f32_e32 v120, v120
	v_cvt_pk_bf16_f32 v152, v158, v159
	v_add_f32_e32 v247, v120, v247
	s_waitcnt lgkmcnt(11)
	v_mfma_f32_32x32x16_bf16 v[66:81], v[142:145], v[174:177], v[66:81]
	ds_read_b128 v[142:145], v241 offset:61440
	v_exp_f32_e32 v121, v121
	v_cvt_pk_bf16_f32 v153, v160, v161
	v_add_f32_e32 v247, v121, v247
	s_waitcnt lgkmcnt(11)
	v_mfma_f32_32x32x16_bf16 v[2:17], v[200:203], v[146:149], v[2:17]
	ds_read_b128 v[200:203], v242 offset:49152
	v_exp_f32_e32 v122, v122
	v_exp_f32_e32 v123, v123
	v_add_f32_e32 v247, v122, v247
	v_add_f32_e32 v247, v123, v247
	s_waitcnt lgkmcnt(11)
	v_mfma_f32_32x32x16_bf16 v[50:65], v[204:207], v[146:149], v[50:65]
	ds_read_b128 v[204:207], v242 offset:53248
	v_exp_f32_e32 v124, v124
	v_exp_f32_e32 v125, v125
	v_add_f32_e32 v247, v124, v247
	v_add_f32_e32 v247, v125, v247
	s_waitcnt lgkmcnt(11)
	v_mfma_f32_32x32x16_bf16 v[34:49], v[208:211], v[146:149], v[34:49]
	ds_read_b128 v[208:211], v242 offset:57344
	v_exp_f32_e32 v126, v126
	v_exp_f32_e32 v127, v127
	v_add_f32_e32 v247, v126, v247
	v_add_f32_e32 v247, v127, v247
	s_waitcnt lgkmcnt(11)
	v_mfma_f32_32x32x16_bf16 v[18:33], v[212:215], v[146:149], v[18:33]
	ds_read_b128 v[212:215], v242 offset:61440
	v_max_i32_e32 v244, v98, v66
	ds_bpermute_b32 v245, v222, v244
	v_exp_f32_e32 v128, v128
	v_exp_f32_e32 v129, v129
	v_add_f32_e32 v247, v128, v247
	v_add_f32_e32 v247, v129, v247
	s_waitcnt lgkmcnt(12)
	v_mfma_f32_32x32x16_bf16 v[2:17], v[180:183], v[150:153], v[2:17]
	v_cvt_pk_bf16_f32 v114, v114, v115
	v_cvt_pk_bf16_f32 v115, v116, v117
	s_waitcnt lgkmcnt(11)
	v_mfma_f32_32x32x16_bf16 v[50:65], v[184:187], v[150:153], v[50:65]
	v_cvt_pk_bf16_f32 v116, v118, v119
	v_cvt_pk_bf16_f32 v117, v120, v121
	s_waitcnt lgkmcnt(10)
	v_mfma_f32_32x32x16_bf16 v[34:49], v[188:191], v[150:153], v[34:49]
	v_cvt_pk_bf16_f32 v118, v122, v123
	v_cvt_pk_bf16_f32 v119, v124, v125
	s_waitcnt lgkmcnt(9)
	v_mfma_f32_32x32x16_bf16 v[18:33], v[192:195], v[150:153], v[18:33]
	v_cvt_pk_bf16_f32 v120, v126, v127
	v_cvt_pk_bf16_f32 v121, v128, v129
	v_add_f32_e32 v238, v238, v247
	s_add_i32 s22, s22, 2
	s_add_i32 s4, s22, -3
	s_cmp_ge_u32 s4, s21
	s_waitcnt vmcnt(0) lgkmcnt(0)
	v_max_i32_e32 v243, v244, v245
	s_barrier
	s_cbranch_scc0 .LBB0_1097
	v_mfma_f32_32x32x16_bf16 v[2:17], v[130:133], v[114:117], v[2:17]
	v_mfma_f32_32x32x16_bf16 v[50:65], v[134:137], v[114:117], v[50:65]
	v_mfma_f32_32x32x16_bf16 v[34:49], v[138:141], v[114:117], v[34:49]
	v_mfma_f32_32x32x16_bf16 v[18:33], v[142:145], v[114:117], v[18:33]
	v_mfma_f32_32x32x16_bf16 v[2:17], v[200:203], v[118:121], v[2:17]
	v_mfma_f32_32x32x16_bf16 v[50:65], v[204:207], v[118:121], v[50:65]
	v_mfma_f32_32x32x16_bf16 v[34:49], v[208:211], v[118:121], v[34:49]
	v_mfma_f32_32x32x16_bf16 v[18:33], v[212:215], v[118:121], v[18:33]
	s_nop 15
